# plus: hand-written GLU epilogue (x loads first, sigmoid under load latency, lane-swap row reduction instead of LDS permutes, early atomics)
# speedup vs baseline: 1.0516x; 1.0040x over previous
; __device__ __forceinline__ float fast_sigmoid(float x) { return __builtin_amdgcn_rcpf(1.0f + __builtin_amdgcn_exp2f(x * -1.44269504f)); }
;     __device__ __forceinline__ void operator()(const Acc& acc, const Unit& u, int wr, int wc, int fr, int fq, LAS unsigned char* lds, f32x4 epar) const {
;         const int c0 = u.pn * 128 + wc * 32 + 8 * fq;
;         f32x4 xv[2][4][2];
; #pragma unroll
;         for (int ai = 0; ai < 2; ++ai)
; #pragma unroll
;             for (int m = 0; m < 4; ++m) { const int r = u.pm * BM + ai * HALF + wr * 64 + m * 16 + fr; const size_t off = (size_t)r * DM + c0;
;                 xv[ai][m][0] = __builtin_nontemporal_load((const f32x4*)(x + off)); xv[ai][m][1] = __builtin_nontemporal_load((const f32x4*)(x + off + 4)); }
; #pragma unroll
;         for (int ai = 0; ai < 2; ++ai)
; #pragma unroll
;             for (int m = 0; m < 4; ++m) { const int r = u.pm * BM + ai * HALF + wr * 64 + m * 16 + fr; const size_t off = (size_t)r * DM + c0;
;                 f32x4 v0 = xv[ai][m][0], v1 = xv[ai][m][1];
;                 const f32x4 za0 = acc[ai][0][m][0], za1 = acc[ai][0][m][1], zg0 = acc[ai][1][m][0], zg1 = acc[ai][1][m][1];
; #pragma unroll
;                 for (int j = 0; j < 4; ++j) { v0[j] += za0[j] * fast_sigmoid(zg0[j]); v1[j] += za1[j] * fast_sigmoid(zg1[j]); }
.LBB0_629:
	v_readlane_b32 s44, v252, 6
	v_readlane_b32 s45, v252, 7
	v_readlane_b32 s46, v252, 8
	v_readlane_b32 s47, v252, 9
	v_readlane_b32 s48, v252, 10
	v_readlane_b32 s49, v252, 11
	v_readlane_b32 s50, v252, 12
	v_readlane_b32 s51, v252, 13
	v_readlane_b32 s52, v252, 14
	v_readlane_b32 s53, v252, 15
	v_readlane_b32 s54, v252, 16
	v_readlane_b32 s55, v252, 17
	v_readlane_b32 s56, v252, 18
	v_readlane_b32 s57, v252, 19
	v_readlane_b32 s58, v252, 20
	v_readlane_b32 s59, v252, 21
	s_mov_b64 s[0:1], exec
	v_lshl_add_u32 v188, s66, 8, v210
	v_lshl_or_b32 v189, s64, 7, v211
	v_lshlrev_b32_e32 v190, 12, v188
	v_lshlrev_b32_e32 v191, 11, v188
	v_lshlrev_b32_e32 v192, 2, v188
	v_lshl_add_u32 v190, v189, 2, v190
	v_lshl_add_u32 v191, v189, 1, v191
	global_load_dwordx4 v[222:225], v190, s[44:45] nt
	global_load_dwordx4 v[218:221], v190, s[44:45] offset:16 nt
	v_add_u32_e32 v193, 0x10000, v190
	global_load_dwordx4 v[180:183], v193, s[44:45] nt
	global_load_dwordx4 v[176:179], v193, s[44:45] offset:16 nt
	v_add_u32_e32 v193, 0x20000, v190
	global_load_dwordx4 v[172:175], v193, s[44:45] nt
	global_load_dwordx4 v[168:171], v193, s[44:45] offset:16 nt
	v_add_u32_e32 v193, 0x30000, v190
	global_load_dwordx4 v[164:167], v193, s[44:45] nt
	global_load_dwordx4 v[160:163], v193, s[44:45] offset:16 nt
	v_add_u32_e32 v193, 0x80000, v190
	global_load_dwordx4 v[156:159], v193, s[44:45] nt
	global_load_dwordx4 v[152:155], v193, s[44:45] offset:16 nt
	v_add_u32_e32 v193, 0x90000, v190
	global_load_dwordx4 v[148:151], v193, s[44:45] nt
	global_load_dwordx4 v[144:147], v193, s[44:45] offset:16 nt
	v_add_u32_e32 v193, 0xa0000, v190
	global_load_dwordx4 v[140:143], v193, s[44:45] nt
	global_load_dwordx4 v[136:139], v193, s[44:45] offset:16 nt
	v_add_u32_e32 v193, 0xb0000, v190
	global_load_dwordx4 v[132:135], v193, s[44:45] nt
	global_load_dwordx4 v[128:131], v193, s[44:45] offset:16 nt
	v_mul_f32_e32 v124, 0xbfb8aa3b, v124
	v_mul_f32_e32 v125, 0xbfb8aa3b, v125
	v_mul_f32_e32 v126, 0xbfb8aa3b, v126
	v_mul_f32_e32 v127, 0xbfb8aa3b, v127
	v_mul_f32_e32 v120, 0xbfb8aa3b, v120
	v_mul_f32_e32 v121, 0xbfb8aa3b, v121
	v_mul_f32_e32 v122, 0xbfb8aa3b, v122
	v_mul_f32_e32 v123, 0xbfb8aa3b, v123
	v_exp_f32_e32 v124, v124
	v_exp_f32_e32 v125, v125
	v_exp_f32_e32 v126, v126
	v_exp_f32_e32 v127, v127
	v_exp_f32_e32 v120, v120
	v_exp_f32_e32 v121, v121
	v_exp_f32_e32 v122, v122
	v_exp_f32_e32 v123, v123
	v_add_f32_e32 v124, 1.0, v124
	v_add_f32_e32 v125, 1.0, v125
	v_add_f32_e32 v126, 1.0, v126
	v_add_f32_e32 v127, 1.0, v127
	v_add_f32_e32 v120, 1.0, v120
	v_add_f32_e32 v121, 1.0, v121
	v_add_f32_e32 v122, 1.0, v122
	v_add_f32_e32 v123, 1.0, v123
	v_rcp_f32_e32 v124, v124
	v_rcp_f32_e32 v125, v125
	v_rcp_f32_e32 v126, v126
	v_rcp_f32_e32 v127, v127
	v_rcp_f32_e32 v120, v120
	v_rcp_f32_e32 v121, v121
	v_rcp_f32_e32 v122, v122
	v_rcp_f32_e32 v123, v123
	v_mul_f32_e32 v108, 0xbfb8aa3b, v108
	v_mul_f32_e32 v109, 0xbfb8aa3b, v109
	v_mul_f32_e32 v110, 0xbfb8aa3b, v110
	v_mul_f32_e32 v111, 0xbfb8aa3b, v111
	v_mul_f32_e32 v104, 0xbfb8aa3b, v104
	v_mul_f32_e32 v105, 0xbfb8aa3b, v105
	v_mul_f32_e32 v106, 0xbfb8aa3b, v106
	v_mul_f32_e32 v107, 0xbfb8aa3b, v107
	v_exp_f32_e32 v108, v108
	v_exp_f32_e32 v109, v109
	v_exp_f32_e32 v110, v110
	v_exp_f32_e32 v111, v111
	v_exp_f32_e32 v104, v104
	v_exp_f32_e32 v105, v105
	v_exp_f32_e32 v106, v106
	v_exp_f32_e32 v107, v107
	v_add_f32_e32 v108, 1.0, v108
	v_add_f32_e32 v109, 1.0, v109
	v_add_f32_e32 v110, 1.0, v110
	v_add_f32_e32 v111, 1.0, v111
	v_add_f32_e32 v104, 1.0, v104
	v_add_f32_e32 v105, 1.0, v105
	v_add_f32_e32 v106, 1.0, v106
	v_add_f32_e32 v107, 1.0, v107
	v_rcp_f32_e32 v108, v108
	v_rcp_f32_e32 v109, v109
	v_rcp_f32_e32 v110, v110
	v_rcp_f32_e32 v111, v111
	v_rcp_f32_e32 v104, v104
	v_rcp_f32_e32 v105, v105
	v_rcp_f32_e32 v106, v106
	v_rcp_f32_e32 v107, v107
	v_mul_f32_e32 v92, 0xbfb8aa3b, v92
	v_mul_f32_e32 v93, 0xbfb8aa3b, v93
	v_mul_f32_e32 v94, 0xbfb8aa3b, v94
	v_mul_f32_e32 v95, 0xbfb8aa3b, v95
	v_mul_f32_e32 v88, 0xbfb8aa3b, v88
	v_mul_f32_e32 v89, 0xbfb8aa3b, v89
	v_mul_f32_e32 v90, 0xbfb8aa3b, v90
	v_mul_f32_e32 v91, 0xbfb8aa3b, v91
	v_exp_f32_e32 v92, v92
	v_exp_f32_e32 v93, v93
	v_exp_f32_e32 v94, v94
	v_exp_f32_e32 v95, v95
	v_exp_f32_e32 v88, v88
	v_exp_f32_e32 v89, v89
	v_exp_f32_e32 v90, v90
	v_exp_f32_e32 v91, v91
	v_add_f32_e32 v92, 1.0, v92
	v_add_f32_e32 v93, 1.0, v93
	v_add_f32_e32 v94, 1.0, v94
	v_add_f32_e32 v95, 1.0, v95
	v_add_f32_e32 v88, 1.0, v88
	v_add_f32_e32 v89, 1.0, v89
	v_add_f32_e32 v90, 1.0, v90
	v_add_f32_e32 v91, 1.0, v91
	v_rcp_f32_e32 v92, v92
	v_rcp_f32_e32 v93, v93
	v_rcp_f32_e32 v94, v94
	v_rcp_f32_e32 v95, v95
	v_rcp_f32_e32 v88, v88
	v_rcp_f32_e32 v89, v89
	v_rcp_f32_e32 v90, v90
	v_rcp_f32_e32 v91, v91
	v_mul_f32_e32 v76, 0xbfb8aa3b, v76
	v_mul_f32_e32 v77, 0xbfb8aa3b, v77
	v_mul_f32_e32 v78, 0xbfb8aa3b, v78
	v_mul_f32_e32 v79, 0xbfb8aa3b, v79
	v_mul_f32_e32 v72, 0xbfb8aa3b, v72
	v_mul_f32_e32 v73, 0xbfb8aa3b, v73
	v_mul_f32_e32 v74, 0xbfb8aa3b, v74
	v_mul_f32_e32 v75, 0xbfb8aa3b, v75
	v_exp_f32_e32 v76, v76
	v_exp_f32_e32 v77, v77
	v_exp_f32_e32 v78, v78
	v_exp_f32_e32 v79, v79
	v_exp_f32_e32 v72, v72
	v_exp_f32_e32 v73, v73
	v_exp_f32_e32 v74, v74
	v_exp_f32_e32 v75, v75
	v_add_f32_e32 v76, 1.0, v76
	v_add_f32_e32 v77, 1.0, v77
	v_add_f32_e32 v78, 1.0, v78
	v_add_f32_e32 v79, 1.0, v79
	v_add_f32_e32 v72, 1.0, v72
	v_add_f32_e32 v73, 1.0, v73
	v_add_f32_e32 v74, 1.0, v74
	v_add_f32_e32 v75, 1.0, v75
	v_rcp_f32_e32 v76, v76
	v_rcp_f32_e32 v77, v77
	v_rcp_f32_e32 v78, v78
	v_rcp_f32_e32 v79, v79
	v_rcp_f32_e32 v72, v72
	v_rcp_f32_e32 v73, v73
	v_rcp_f32_e32 v74, v74
	v_rcp_f32_e32 v75, v75
; __device__ __forceinline__ unsigned cvt_pk_bf16(float lo, float hi) { unsigned r; asm volatile("v_cvt_pk_bf16_f32 %0, %1, %2" : "=v"(r) : "v"(lo), "v"(hi)); return r; }
; __device__ __forceinline__ float fast_sigmoid(float x) { return __builtin_amdgcn_rcpf(1.0f + __builtin_amdgcn_exp2f(x * -1.44269504f)); }
;     __device__ __forceinline__ void operator()(const Acc& acc, const Unit& u, int wr, int wc, int fr, int fq, LAS unsigned char* lds, f32x4 epar) const {
;     ...
;         for (int ai = 0; ai < 2; ++ai)
; #pragma unroll
;             for (int m = 0; m < 4; ++m) { const int r = u.pm * BM + ai * HALF + wr * 64 + m * 16 + fr; const size_t off = (size_t)r * DM + c0;
;                 f32x4 v0 = xv[ai][m][0], v1 = xv[ai][m][1];
;                 const f32x4 za0 = acc[ai][0][m][0], za1 = acc[ai][0][m][1], zg0 = acc[ai][1][m][0], zg1 = acc[ai][1][m][1];
; #pragma unroll
;                 for (int j = 0; j < 4; ++j) { v0[j] += za0[j] * fast_sigmoid(zg0[j]); v1[j] += za1[j] * fast_sigmoid(zg1[j]); }
;                 u32x4 w; w.x = cvt_pk_bf16(v0[0], v0[1]); w.y = cvt_pk_bf16(v0[2], v0[3]); w.z = cvt_pk_bf16(v1[0], v1[1]); w.w = cvt_pk_bf16(v1[2], v1[3]);
;                 *(u32x4*)(HB + off) = w;
;                 float s = (v0[0] * v0[0] + v0[1] * v0[1]) + (v0[2] * v0[2] + v0[3] * v0[3]) + (v1[0] * v1[0] + v1[1] * v1[1]) + (v1[2] * v1[2] + v1[3] * v1[3]);
;                 s += __shfl_xor(s, 16); s += __shfl_xor(s, 32);
;                 if (fq == 0) unsafeAtomicAdd(ssq + r, s); }
	v_mul_f32_e32 v60, 0xbfb8aa3b, v60
	v_mul_f32_e32 v61, 0xbfb8aa3b, v61
	v_mul_f32_e32 v62, 0xbfb8aa3b, v62
	v_mul_f32_e32 v63, 0xbfb8aa3b, v63
	v_mul_f32_e32 v56, 0xbfb8aa3b, v56
	v_mul_f32_e32 v57, 0xbfb8aa3b, v57
	v_mul_f32_e32 v58, 0xbfb8aa3b, v58
	v_mul_f32_e32 v59, 0xbfb8aa3b, v59
	v_exp_f32_e32 v60, v60
	v_exp_f32_e32 v61, v61
	v_exp_f32_e32 v62, v62
	v_exp_f32_e32 v63, v63
	v_exp_f32_e32 v56, v56
	v_exp_f32_e32 v57, v57
	v_exp_f32_e32 v58, v58
	v_exp_f32_e32 v59, v59
	v_add_f32_e32 v60, 1.0, v60
	v_add_f32_e32 v61, 1.0, v61
	v_add_f32_e32 v62, 1.0, v62
	v_add_f32_e32 v63, 1.0, v63
	v_add_f32_e32 v56, 1.0, v56
	v_add_f32_e32 v57, 1.0, v57
	v_add_f32_e32 v58, 1.0, v58
	v_add_f32_e32 v59, 1.0, v59
	v_rcp_f32_e32 v60, v60
	v_rcp_f32_e32 v61, v61
	v_rcp_f32_e32 v62, v62
	v_rcp_f32_e32 v63, v63
	v_rcp_f32_e32 v56, v56
	v_rcp_f32_e32 v57, v57
	v_rcp_f32_e32 v58, v58
	v_rcp_f32_e32 v59, v59
	v_mul_f32_e32 v44, 0xbfb8aa3b, v44
	v_mul_f32_e32 v45, 0xbfb8aa3b, v45
	v_mul_f32_e32 v46, 0xbfb8aa3b, v46
	v_mul_f32_e32 v47, 0xbfb8aa3b, v47
	v_mul_f32_e32 v40, 0xbfb8aa3b, v40
	v_mul_f32_e32 v41, 0xbfb8aa3b, v41
	v_mul_f32_e32 v42, 0xbfb8aa3b, v42
	v_mul_f32_e32 v43, 0xbfb8aa3b, v43
	v_exp_f32_e32 v44, v44
	v_exp_f32_e32 v45, v45
	v_exp_f32_e32 v46, v46
	v_exp_f32_e32 v47, v47
	v_exp_f32_e32 v40, v40
	v_exp_f32_e32 v41, v41
	v_exp_f32_e32 v42, v42
	v_exp_f32_e32 v43, v43
	v_add_f32_e32 v44, 1.0, v44
	v_add_f32_e32 v45, 1.0, v45
	v_add_f32_e32 v46, 1.0, v46
	v_add_f32_e32 v47, 1.0, v47
	v_add_f32_e32 v40, 1.0, v40
	v_add_f32_e32 v41, 1.0, v41
	v_add_f32_e32 v42, 1.0, v42
	v_add_f32_e32 v43, 1.0, v43
	v_rcp_f32_e32 v44, v44
	v_rcp_f32_e32 v45, v45
	v_rcp_f32_e32 v46, v46
	v_rcp_f32_e32 v47, v47
	v_rcp_f32_e32 v40, v40
	v_rcp_f32_e32 v41, v41
	v_rcp_f32_e32 v42, v42
	v_rcp_f32_e32 v43, v43
	v_mul_f32_e32 v28, 0xbfb8aa3b, v28
	v_mul_f32_e32 v29, 0xbfb8aa3b, v29
	v_mul_f32_e32 v30, 0xbfb8aa3b, v30
	v_mul_f32_e32 v31, 0xbfb8aa3b, v31
	v_mul_f32_e32 v24, 0xbfb8aa3b, v24
	v_mul_f32_e32 v25, 0xbfb8aa3b, v25
	v_mul_f32_e32 v26, 0xbfb8aa3b, v26
	v_mul_f32_e32 v27, 0xbfb8aa3b, v27
	v_exp_f32_e32 v28, v28
	v_exp_f32_e32 v29, v29
	v_exp_f32_e32 v30, v30
	v_exp_f32_e32 v31, v31
	v_exp_f32_e32 v24, v24
	v_exp_f32_e32 v25, v25
	v_exp_f32_e32 v26, v26
	v_exp_f32_e32 v27, v27
	v_add_f32_e32 v28, 1.0, v28
	v_add_f32_e32 v29, 1.0, v29
	v_add_f32_e32 v30, 1.0, v30
	v_add_f32_e32 v31, 1.0, v31
	v_add_f32_e32 v24, 1.0, v24
	v_add_f32_e32 v25, 1.0, v25
	v_add_f32_e32 v26, 1.0, v26
	v_add_f32_e32 v27, 1.0, v27
	v_rcp_f32_e32 v28, v28
	v_rcp_f32_e32 v29, v29
	v_rcp_f32_e32 v30, v30
	v_rcp_f32_e32 v31, v31
	v_rcp_f32_e32 v24, v24
	v_rcp_f32_e32 v25, v25
	v_rcp_f32_e32 v26, v26
	v_rcp_f32_e32 v27, v27
	v_mul_f32_e32 v12, 0xbfb8aa3b, v12
	v_mul_f32_e32 v13, 0xbfb8aa3b, v13
	v_mul_f32_e32 v14, 0xbfb8aa3b, v14
	v_mul_f32_e32 v15, 0xbfb8aa3b, v15
	v_mul_f32_e32 v8, 0xbfb8aa3b, v8
	v_mul_f32_e32 v9, 0xbfb8aa3b, v9
	v_mul_f32_e32 v10, 0xbfb8aa3b, v10
	v_mul_f32_e32 v11, 0xbfb8aa3b, v11
	v_exp_f32_e32 v12, v12
	v_exp_f32_e32 v13, v13
	v_exp_f32_e32 v14, v14
	v_exp_f32_e32 v15, v15
	v_exp_f32_e32 v8, v8
	v_exp_f32_e32 v9, v9
	v_exp_f32_e32 v10, v10
	v_exp_f32_e32 v11, v11
	v_add_f32_e32 v12, 1.0, v12
	v_add_f32_e32 v13, 1.0, v13
	v_add_f32_e32 v14, 1.0, v14
	v_add_f32_e32 v15, 1.0, v15
	v_add_f32_e32 v8, 1.0, v8
	v_add_f32_e32 v9, 1.0, v9
	v_add_f32_e32 v10, 1.0, v10
	v_add_f32_e32 v11, 1.0, v11
	v_rcp_f32_e32 v12, v12
	v_rcp_f32_e32 v13, v13
	v_rcp_f32_e32 v14, v14
	v_rcp_f32_e32 v15, v15
	v_rcp_f32_e32 v8, v8
	v_rcp_f32_e32 v9, v9
	v_rcp_f32_e32 v10, v10
	v_rcp_f32_e32 v11, v11
	s_nop 0
	s_waitcnt vmcnt(14)
	v_fma_f32 v222, v124, v112, v222
	v_fma_f32 v223, v125, v113, v223
	v_fma_f32 v224, v126, v114, v224
	v_fma_f32 v225, v127, v115, v225
	v_fma_f32 v218, v120, v116, v218
	v_fma_f32 v219, v121, v117, v219
	v_fma_f32 v220, v122, v118, v220
	v_fma_f32 v221, v123, v119, v221
	v_mul_f32_e32 v124, v222, v222
	v_mul_f32_e32 v125, v224, v224
	v_mul_f32_e32 v126, v218, v218
	v_mul_f32_e32 v127, v220, v220
	v_fmac_f32_e32 v124, v223, v223
	v_fmac_f32_e32 v125, v225, v225
	v_fmac_f32_e32 v126, v219, v219
	v_fmac_f32_e32 v127, v221, v221
	v_cvt_pk_bf16_f32 v112, v222, v223
	v_cvt_pk_bf16_f32 v113, v224, v225
	v_cvt_pk_bf16_f32 v114, v218, v219
	v_cvt_pk_bf16_f32 v115, v220, v221
	v_add_f32_e32 v124, v124, v125
	v_add_f32_e32 v126, v126, v127
	v_add_f32_e32 v194, v124, v126
	global_store_dwordx4 v191, v[112:115], s[20:21]
	v_mov_b32_e32 v202, v194
	s_nop 0
	s_nop 0
	v_permlane16_swap_b32_e32 v194, v202
	v_add_f32_e32 v194, v194, v202
	v_mov_b32_e32 v202, v194
	s_nop 1
	v_permlane32_swap_b32_e32 v194, v202
	v_add_f32_e32 v194, v194, v202
	s_and_b64 exec, exec, s[4:5]
	global_atomic_add_f32 v192, v194, s[60:61]
	s_mov_b64 exec, s[0:1]
	s_waitcnt vmcnt(14)
	v_fma_f32 v180, v108, v100, v180
	v_fma_f32 v181, v109, v101, v181
	v_fma_f32 v182, v110, v102, v182
	v_fma_f32 v183, v111, v103, v183
	v_fma_f32 v176, v104, v96, v176
	v_fma_f32 v177, v105, v97, v177
	v_fma_f32 v178, v106, v98, v178
	v_fma_f32 v179, v107, v99, v179
	v_mul_f32_e32 v108, v180, v180
	v_mul_f32_e32 v109, v182, v182
	v_mul_f32_e32 v110, v176, v176
	v_mul_f32_e32 v111, v178, v178
	v_fmac_f32_e32 v108, v181, v181
	v_fmac_f32_e32 v109, v183, v183
	v_fmac_f32_e32 v110, v177, v177
	v_fmac_f32_e32 v111, v179, v179
	v_cvt_pk_bf16_f32 v100, v180, v181
	v_cvt_pk_bf16_f32 v101, v182, v183
	v_cvt_pk_bf16_f32 v102, v176, v177
	v_cvt_pk_bf16_f32 v103, v178, v179
	v_add_f32_e32 v108, v108, v109
	v_add_f32_e32 v110, v110, v111
	v_add_u32_e32 v193, 0x8000, v191
	v_add_f32_e32 v195, v108, v110
	global_store_dwordx4 v193, v[100:103], s[20:21]
	v_mov_b32_e32 v203, v195
	v_add_u32_e32 v193, 0x40, v192
	s_nop 0
	v_permlane16_swap_b32_e32 v195, v203
	v_add_f32_e32 v195, v195, v203
	v_mov_b32_e32 v203, v195
	s_nop 1
	v_permlane32_swap_b32_e32 v195, v203
	v_add_f32_e32 v195, v195, v203
	s_and_b64 exec, exec, s[4:5]
	global_atomic_add_f32 v193, v195, s[60:61]
	s_mov_b64 exec, s[0:1]
	s_waitcnt vmcnt(14)
; __device__ __forceinline__ unsigned cvt_pk_bf16(float lo, float hi) { unsigned r; asm volatile("v_cvt_pk_bf16_f32 %0, %1, %2" : "=v"(r) : "v"(lo), "v"(hi)); return r; }
; __device__ __forceinline__ float fast_sigmoid(float x) { return __builtin_amdgcn_rcpf(1.0f + __builtin_amdgcn_exp2f(x * -1.44269504f)); }
;     __device__ __forceinline__ void operator()(const Acc& acc, const Unit& u, int wr, int wc, int fr, int fq, LAS unsigned char* lds, f32x4 epar) const {
;     ...
;         for (int ai = 0; ai < 2; ++ai)
; #pragma unroll
;             for (int m = 0; m < 4; ++m) { const int r = u.pm * BM + ai * HALF + wr * 64 + m * 16 + fr; const size_t off = (size_t)r * DM + c0;
;                 f32x4 v0 = xv[ai][m][0], v1 = xv[ai][m][1];
;                 const f32x4 za0 = acc[ai][0][m][0], za1 = acc[ai][0][m][1], zg0 = acc[ai][1][m][0], zg1 = acc[ai][1][m][1];
; #pragma unroll
;                 for (int j = 0; j < 4; ++j) { v0[j] += za0[j] * fast_sigmoid(zg0[j]); v1[j] += za1[j] * fast_sigmoid(zg1[j]); }
;                 u32x4 w; w.x = cvt_pk_bf16(v0[0], v0[1]); w.y = cvt_pk_bf16(v0[2], v0[3]); w.z = cvt_pk_bf16(v1[0], v1[1]); w.w = cvt_pk_bf16(v1[2], v1[3]);
;                 *(u32x4*)(HB + off) = w;
;                 float s = (v0[0] * v0[0] + v0[1] * v0[1]) + (v0[2] * v0[2] + v0[3] * v0[3]) + (v1[0] * v1[0] + v1[1] * v1[1]) + (v1[2] * v1[2] + v1[3] * v1[3]);
;                 s += __shfl_xor(s, 16); s += __shfl_xor(s, 32);
;                 if (fq == 0) unsafeAtomicAdd(ssq + r, s); }
	v_fma_f32 v172, v92, v84, v172
	v_fma_f32 v173, v93, v85, v173
	v_fma_f32 v174, v94, v86, v174
	v_fma_f32 v175, v95, v87, v175
	v_fma_f32 v168, v88, v80, v168
	v_fma_f32 v169, v89, v81, v169
	v_fma_f32 v170, v90, v82, v170
	v_fma_f32 v171, v91, v83, v171
	v_mul_f32_e32 v92, v172, v172
	v_mul_f32_e32 v93, v174, v174
	v_mul_f32_e32 v94, v168, v168
	v_mul_f32_e32 v95, v170, v170
	v_fmac_f32_e32 v92, v173, v173
	v_fmac_f32_e32 v93, v175, v175
	v_fmac_f32_e32 v94, v169, v169
	v_fmac_f32_e32 v95, v171, v171
	v_cvt_pk_bf16_f32 v84, v172, v173
	v_cvt_pk_bf16_f32 v85, v174, v175
	v_cvt_pk_bf16_f32 v86, v168, v169
	v_cvt_pk_bf16_f32 v87, v170, v171
	v_add_f32_e32 v92, v92, v93
	v_add_f32_e32 v94, v94, v95
	v_add_u32_e32 v193, 0x10000, v191
	v_add_f32_e32 v196, v92, v94
	global_store_dwordx4 v193, v[84:87], s[20:21]
	v_mov_b32_e32 v204, v196
	v_add_u32_e32 v193, 0x80, v192
	s_nop 0
	v_permlane16_swap_b32_e32 v196, v204
	v_add_f32_e32 v196, v196, v204
	v_mov_b32_e32 v204, v196
	s_nop 1
	v_permlane32_swap_b32_e32 v196, v204
	v_add_f32_e32 v196, v196, v204
	s_and_b64 exec, exec, s[4:5]
	global_atomic_add_f32 v193, v196, s[60:61]
	s_mov_b64 exec, s[0:1]
	s_waitcnt vmcnt(14)
	v_fma_f32 v164, v76, v68, v164
	v_fma_f32 v165, v77, v69, v165
	v_fma_f32 v166, v78, v70, v166
	v_fma_f32 v167, v79, v71, v167
	v_fma_f32 v160, v72, v64, v160
	v_fma_f32 v161, v73, v65, v161
	v_fma_f32 v162, v74, v66, v162
	v_fma_f32 v163, v75, v67, v163
	v_mul_f32_e32 v76, v164, v164
	v_mul_f32_e32 v77, v166, v166
	v_mul_f32_e32 v78, v160, v160
	v_mul_f32_e32 v79, v162, v162
	v_fmac_f32_e32 v76, v165, v165
	v_fmac_f32_e32 v77, v167, v167
	v_fmac_f32_e32 v78, v161, v161
	v_fmac_f32_e32 v79, v163, v163
	v_cvt_pk_bf16_f32 v68, v164, v165
	v_cvt_pk_bf16_f32 v69, v166, v167
	v_cvt_pk_bf16_f32 v70, v160, v161
	v_cvt_pk_bf16_f32 v71, v162, v163
	v_add_f32_e32 v76, v76, v77
	v_add_f32_e32 v78, v78, v79
	v_add_u32_e32 v193, 0x18000, v191
	v_add_f32_e32 v197, v76, v78
	global_store_dwordx4 v193, v[68:71], s[20:21]
	v_mov_b32_e32 v205, v197
	v_add_u32_e32 v193, 0xc0, v192
	s_nop 0
	v_permlane16_swap_b32_e32 v197, v205
	v_add_f32_e32 v197, v197, v205
	v_mov_b32_e32 v205, v197
	s_nop 1
	v_permlane32_swap_b32_e32 v197, v205
	v_add_f32_e32 v197, v197, v205
	s_and_b64 exec, exec, s[4:5]
	global_atomic_add_f32 v193, v197, s[60:61]
	s_mov_b64 exec, s[0:1]
	s_waitcnt vmcnt(14)
	v_fma_f32 v156, v60, v52, v156
	v_fma_f32 v157, v61, v53, v157
	v_fma_f32 v158, v62, v54, v158
	v_fma_f32 v159, v63, v55, v159
	v_fma_f32 v152, v56, v48, v152
	v_fma_f32 v153, v57, v49, v153
	v_fma_f32 v154, v58, v50, v154
	v_fma_f32 v155, v59, v51, v155
	v_mul_f32_e32 v60, v156, v156
	v_mul_f32_e32 v61, v158, v158
	v_mul_f32_e32 v62, v152, v152
	v_mul_f32_e32 v63, v154, v154
	v_fmac_f32_e32 v60, v157, v157
	v_fmac_f32_e32 v61, v159, v159
	v_fmac_f32_e32 v62, v153, v153
	v_fmac_f32_e32 v63, v155, v155
	v_cvt_pk_bf16_f32 v52, v156, v157
	v_cvt_pk_bf16_f32 v53, v158, v159
	v_cvt_pk_bf16_f32 v54, v152, v153
	v_cvt_pk_bf16_f32 v55, v154, v155
	v_add_f32_e32 v60, v60, v61
	v_add_f32_e32 v62, v62, v63
	v_add_u32_e32 v193, 0x40000, v191
	v_add_f32_e32 v198, v60, v62
	global_store_dwordx4 v193, v[52:55], s[20:21]
	v_mov_b32_e32 v124, v198
	v_add_u32_e32 v193, 0x200, v192
	s_nop 0
	v_permlane16_swap_b32_e32 v198, v124
	v_add_f32_e32 v198, v198, v124
	v_mov_b32_e32 v124, v198
	s_nop 1
	v_permlane32_swap_b32_e32 v198, v124
	v_add_f32_e32 v198, v198, v124
	s_and_b64 exec, exec, s[4:5]
	global_atomic_add_f32 v193, v198, s[60:61]
	s_mov_b64 exec, s[0:1]
	s_waitcnt vmcnt(14)
; __device__ __forceinline__ unsigned cvt_pk_bf16(float lo, float hi) { unsigned r; asm volatile("v_cvt_pk_bf16_f32 %0, %1, %2" : "=v"(r) : "v"(lo), "v"(hi)); return r; }
; __device__ __forceinline__ float fast_sigmoid(float x) { return __builtin_amdgcn_rcpf(1.0f + __builtin_amdgcn_exp2f(x * -1.44269504f)); }
;     __device__ __forceinline__ void operator()(const Acc& acc, const Unit& u, int wr, int wc, int fr, int fq, LAS unsigned char* lds, f32x4 epar) const {
;     ...
;         for (int ai = 0; ai < 2; ++ai)
; #pragma unroll
;             for (int m = 0; m < 4; ++m) { const int r = u.pm * BM + ai * HALF + wr * 64 + m * 16 + fr; const size_t off = (size_t)r * DM + c0;
;                 f32x4 v0 = xv[ai][m][0], v1 = xv[ai][m][1];
;                 const f32x4 za0 = acc[ai][0][m][0], za1 = acc[ai][0][m][1], zg0 = acc[ai][1][m][0], zg1 = acc[ai][1][m][1];
; #pragma unroll
;                 for (int j = 0; j < 4; ++j) { v0[j] += za0[j] * fast_sigmoid(zg0[j]); v1[j] += za1[j] * fast_sigmoid(zg1[j]); }
;                 u32x4 w; w.x = cvt_pk_bf16(v0[0], v0[1]); w.y = cvt_pk_bf16(v0[2], v0[3]); w.z = cvt_pk_bf16(v1[0], v1[1]); w.w = cvt_pk_bf16(v1[2], v1[3]);
;                 *(u32x4*)(HB + off) = w;
;                 float s = (v0[0] * v0[0] + v0[1] * v0[1]) + (v0[2] * v0[2] + v0[3] * v0[3]) + (v1[0] * v1[0] + v1[1] * v1[1]) + (v1[2] * v1[2] + v1[3] * v1[3]);
;                 s += __shfl_xor(s, 16); s += __shfl_xor(s, 32);
;                 if (fq == 0) unsafeAtomicAdd(ssq + r, s); }
	v_fma_f32 v148, v44, v36, v148
	v_fma_f32 v149, v45, v37, v149
	v_fma_f32 v150, v46, v38, v150
	v_fma_f32 v151, v47, v39, v151
	v_fma_f32 v144, v40, v32, v144
	v_fma_f32 v145, v41, v33, v145
	v_fma_f32 v146, v42, v34, v146
	v_fma_f32 v147, v43, v35, v147
	v_mul_f32_e32 v44, v148, v148
	v_mul_f32_e32 v45, v150, v150
	v_mul_f32_e32 v46, v144, v144
	v_mul_f32_e32 v47, v146, v146
	v_fmac_f32_e32 v44, v149, v149
	v_fmac_f32_e32 v45, v151, v151
	v_fmac_f32_e32 v46, v145, v145
	v_fmac_f32_e32 v47, v147, v147
	v_cvt_pk_bf16_f32 v36, v148, v149
	v_cvt_pk_bf16_f32 v37, v150, v151
	v_cvt_pk_bf16_f32 v38, v144, v145
	v_cvt_pk_bf16_f32 v39, v146, v147
	v_add_f32_e32 v44, v44, v45
	v_add_f32_e32 v46, v46, v47
	v_add_u32_e32 v193, 0x48000, v191
	v_add_f32_e32 v199, v44, v46
	global_store_dwordx4 v193, v[36:39], s[20:21]
	v_mov_b32_e32 v125, v199
	v_add_u32_e32 v193, 0x240, v192
	s_nop 0
	v_permlane16_swap_b32_e32 v199, v125
	v_add_f32_e32 v199, v199, v125
	v_mov_b32_e32 v125, v199
	s_nop 1
	v_permlane32_swap_b32_e32 v199, v125
	v_add_f32_e32 v199, v199, v125
	s_and_b64 exec, exec, s[4:5]
	global_atomic_add_f32 v193, v199, s[60:61]
	s_mov_b64 exec, s[0:1]
	s_waitcnt vmcnt(14)
	v_fma_f32 v140, v28, v20, v140
	v_fma_f32 v141, v29, v21, v141
	v_fma_f32 v142, v30, v22, v142
	v_fma_f32 v143, v31, v23, v143
	v_fma_f32 v136, v24, v16, v136
	v_fma_f32 v137, v25, v17, v137
	v_fma_f32 v138, v26, v18, v138
	v_fma_f32 v139, v27, v19, v139
	v_mul_f32_e32 v28, v140, v140
	v_mul_f32_e32 v29, v142, v142
	v_mul_f32_e32 v30, v136, v136
	v_mul_f32_e32 v31, v138, v138
	v_fmac_f32_e32 v28, v141, v141
	v_fmac_f32_e32 v29, v143, v143
	v_fmac_f32_e32 v30, v137, v137
	v_fmac_f32_e32 v31, v139, v139
	v_cvt_pk_bf16_f32 v20, v140, v141
	v_cvt_pk_bf16_f32 v21, v142, v143
	v_cvt_pk_bf16_f32 v22, v136, v137
	v_cvt_pk_bf16_f32 v23, v138, v139
	v_add_f32_e32 v28, v28, v29
	v_add_f32_e32 v30, v30, v31
	v_add_u32_e32 v193, 0x50000, v191
	v_add_f32_e32 v200, v28, v30
	global_store_dwordx4 v193, v[20:23], s[20:21]
	v_mov_b32_e32 v126, v200
	v_add_u32_e32 v193, 0x280, v192
	s_nop 0
	v_permlane16_swap_b32_e32 v200, v126
	v_add_f32_e32 v200, v200, v126
	v_mov_b32_e32 v126, v200
	s_nop 1
	v_permlane32_swap_b32_e32 v200, v126
	v_add_f32_e32 v200, v200, v126
	s_and_b64 exec, exec, s[4:5]
	global_atomic_add_f32 v193, v200, s[60:61]
	s_mov_b64 exec, s[0:1]
	s_waitcnt vmcnt(14)
	v_fma_f32 v132, v12, v4, v132
	v_fma_f32 v133, v13, v5, v133
	v_fma_f32 v134, v14, v6, v134
	v_fma_f32 v135, v15, v7, v135
	v_fma_f32 v128, v8, v0, v128
	v_fma_f32 v129, v9, v1, v129
	v_fma_f32 v130, v10, v2, v130
	v_fma_f32 v131, v11, v3, v131
	v_mul_f32_e32 v12, v132, v132
	v_mul_f32_e32 v13, v134, v134
	v_mul_f32_e32 v14, v128, v128
	v_mul_f32_e32 v15, v130, v130
	v_fmac_f32_e32 v12, v133, v133
	v_fmac_f32_e32 v13, v135, v135
	v_fmac_f32_e32 v14, v129, v129
	v_fmac_f32_e32 v15, v131, v131
	v_cvt_pk_bf16_f32 v4, v132, v133
	v_cvt_pk_bf16_f32 v5, v134, v135
	v_cvt_pk_bf16_f32 v6, v128, v129
	v_cvt_pk_bf16_f32 v7, v130, v131
	v_add_f32_e32 v12, v12, v13
	v_add_f32_e32 v14, v14, v15
	v_add_u32_e32 v193, 0x58000, v191
	v_add_f32_e32 v201, v12, v14
	global_store_dwordx4 v193, v[4:7], s[20:21]
	v_mov_b32_e32 v127, v201
	v_add_u32_e32 v193, 0x2c0, v192
	s_nop 0
	v_permlane16_swap_b32_e32 v201, v127
	v_add_f32_e32 v201, v201, v127
	v_mov_b32_e32 v127, v201
	s_nop 1
	v_permlane32_swap_b32_e32 v201, v127
	v_add_f32_e32 v201, v201, v127
	s_and_b64 exec, exec, s[4:5]
	global_atomic_add_f32 v193, v201, s[60:61]
	s_mov_b64 exec, s[0:1]
	s_branch .LBB0_618
